# speedup vs baseline: 1.0009x; 1.0009x over previous
; __device__ __forceinline__ float bflo(unsigned u) { return __uint_as_float(u << 16); }
; __device__ __forceinline__ float bfhi(unsigned u) { return __uint_as_float(u & 0xffff0000u); }
; __device__ __forceinline__ void epilogue(const Params& p, int mode, const float* resid, int r, int c, f32x4 v) {
;     ...
;   } else if (mode == EPI_RESID_B) {
;     u32x2 xr = *reinterpret_cast<const u32x2*>(WSP(u16, WS_HB) + (long)c * D + r);
;     f32x4 o = {ALPHA * bflo(xr[0]) + v[0], ALPHA * bfhi(xr[0]) + v[1], ALPHA * bflo(xr[1]) + v[2], ALPHA * bfhi(xr[1]) + v[3]};
;     *reinterpret_cast<f32x4*>(WSP(float, WS_PRE) + (long)c * D + r) = o;
; __device__ __forceinline__ void gemm_run(const Params& p, const u16* A1, const u16* Bt1, int M1, int N1, int K, int mode1,
;                                          const float* resid, u16* shm, const u16* A2, const u16* Bt2, int M2, int N2,
;                                          int mode2) {
;     ...
; #pragma unroll
;     for (int ai = 0; ai < 2; ++ai)
; #pragma unroll
;       for (int bj = 0; bj < 2; ++bj)
; #pragma unroll
;         for (int m = 0; m < 4; ++m)
; #pragma unroll
;           for (int n = 0; n < 2; ++n)
;             epilogue(p, mode, resid, brow + ai * HALF + wr * 64 + m * 16 + fq * 4, bcol + bj * HALF + wc * 32 + n * 16 + fr,
;                      acc[ai][bj][m][n]);
.Lepi5_start:
	v_add_u32_e32 v0, s74, v187
	v_or_b32_e32 v0, v0, v188
	v_or_b32_e32 v130, s91, v189
	v_lshlrev_b32_e32 v0, 1, v0
	v_lshl_add_u32 v194, v130, 13, v0
	v_add_u32_e32 v195, 0x20000, v194
	v_add_u32_e32 v196, 0x100000, v194
	v_add_u32_e32 v197, 0x120000, v194
	v_lshlrev_b32_e32 v198, 1, v194
	v_lshlrev_b32_e32 v199, 1, v195
	v_lshlrev_b32_e32 v200, 1, v196
	v_lshlrev_b32_e32 v201, 1, v197
	global_load_dwordx2 v[136:137], v194, s[40:41] offset:0
	global_load_dwordx2 v[138:139], v195, s[40:41] offset:0
	global_load_dwordx2 v[140:141], v194, s[40:41] offset:32
	global_load_dwordx2 v[142:143], v195, s[40:41] offset:32
	global_load_dwordx2 v[144:145], v194, s[40:41] offset:64
	global_load_dwordx2 v[146:147], v195, s[40:41] offset:64
	global_load_dwordx2 v[148:149], v194, s[40:41] offset:96
	global_load_dwordx2 v[150:151], v195, s[40:41] offset:96
	global_load_dwordx2 v[152:153], v196, s[40:41] offset:0
	global_load_dwordx2 v[154:155], v197, s[40:41] offset:0
	global_load_dwordx2 v[156:157], v196, s[40:41] offset:32
	global_load_dwordx2 v[158:159], v197, s[40:41] offset:32
	global_load_dwordx2 v[160:161], v196, s[40:41] offset:64
	global_load_dwordx2 v[162:163], v197, s[40:41] offset:64
	global_load_dwordx2 v[190:191], v196, s[40:41] offset:96
	global_load_dwordx2 v[192:193], v197, s[40:41] offset:96
	s_waitcnt vmcnt(15)
	v_lshlrev_b32_e32 v202, 16, v136
	v_and_b32_e32 v203, 0xffff0000, v136
	v_lshlrev_b32_e32 v204, 16, v137
	v_and_b32_e32 v205, 0xffff0000, v137
	v_pk_fma_f32 v[126:127], v[202:203], s[76:77], v[126:127] op_sel_hi:[1,0,1]
	v_pk_fma_f32 v[128:129], v[204:205], s[76:77], v[128:129] op_sel_hi:[1,0,1]
	global_store_dwordx4 v198, v[126:129], s[42:43] offset:0 nt
	global_load_dwordx2 v[136:137], v194, s[40:41] offset:256
	s_waitcnt vmcnt(16)
	v_lshlrev_b32_e32 v206, 16, v138
	v_and_b32_e32 v207, 0xffff0000, v138
	v_lshlrev_b32_e32 v208, 16, v139
	v_and_b32_e32 v209, 0xffff0000, v139
	v_pk_fma_f32 v[122:123], v[206:207], s[76:77], v[122:123] op_sel_hi:[1,0,1]
	v_pk_fma_f32 v[124:125], v[208:209], s[76:77], v[124:125] op_sel_hi:[1,0,1]
	global_store_dwordx4 v199, v[122:125], s[42:43] offset:0 nt
	global_load_dwordx2 v[138:139], v195, s[40:41] offset:256
	s_waitcnt vmcnt(17)
	v_lshlrev_b32_e32 v202, 16, v140
	v_and_b32_e32 v203, 0xffff0000, v140
	v_lshlrev_b32_e32 v204, 16, v141
	v_and_b32_e32 v205, 0xffff0000, v141
	v_pk_fma_f32 v[118:119], v[202:203], s[76:77], v[118:119] op_sel_hi:[1,0,1]
	v_pk_fma_f32 v[120:121], v[204:205], s[76:77], v[120:121] op_sel_hi:[1,0,1]
	global_store_dwordx4 v198, v[118:121], s[42:43] offset:64 nt
	global_load_dwordx2 v[140:141], v194, s[40:41] offset:288
	s_waitcnt vmcnt(18)
	v_lshlrev_b32_e32 v206, 16, v142
	v_and_b32_e32 v207, 0xffff0000, v142
	v_lshlrev_b32_e32 v208, 16, v143
	v_and_b32_e32 v209, 0xffff0000, v143
	v_pk_fma_f32 v[114:115], v[206:207], s[76:77], v[114:115] op_sel_hi:[1,0,1]
	v_pk_fma_f32 v[116:117], v[208:209], s[76:77], v[116:117] op_sel_hi:[1,0,1]
	global_store_dwordx4 v199, v[114:117], s[42:43] offset:64 nt
	global_load_dwordx2 v[142:143], v195, s[40:41] offset:288
	s_waitcnt vmcnt(19)
	v_lshlrev_b32_e32 v202, 16, v144
	v_and_b32_e32 v203, 0xffff0000, v144
	v_lshlrev_b32_e32 v204, 16, v145
	v_and_b32_e32 v205, 0xffff0000, v145
	v_pk_fma_f32 v[110:111], v[202:203], s[76:77], v[110:111] op_sel_hi:[1,0,1]
	v_pk_fma_f32 v[112:113], v[204:205], s[76:77], v[112:113] op_sel_hi:[1,0,1]
	global_store_dwordx4 v198, v[110:113], s[42:43] offset:128 nt
	global_load_dwordx2 v[144:145], v194, s[40:41] offset:320
	s_waitcnt vmcnt(20)
	v_lshlrev_b32_e32 v206, 16, v146
	v_and_b32_e32 v207, 0xffff0000, v146
	v_lshlrev_b32_e32 v208, 16, v147
	v_and_b32_e32 v209, 0xffff0000, v147
	v_pk_fma_f32 v[106:107], v[206:207], s[76:77], v[106:107] op_sel_hi:[1,0,1]
	v_pk_fma_f32 v[108:109], v[208:209], s[76:77], v[108:109] op_sel_hi:[1,0,1]
	global_store_dwordx4 v199, v[106:109], s[42:43] offset:128 nt
	global_load_dwordx2 v[146:147], v195, s[40:41] offset:320
	s_waitcnt vmcnt(21)
	v_lshlrev_b32_e32 v202, 16, v148
	v_and_b32_e32 v203, 0xffff0000, v148
	v_lshlrev_b32_e32 v204, 16, v149
	v_and_b32_e32 v205, 0xffff0000, v149
	v_pk_fma_f32 v[102:103], v[202:203], s[76:77], v[102:103] op_sel_hi:[1,0,1]
	v_pk_fma_f32 v[104:105], v[204:205], s[76:77], v[104:105] op_sel_hi:[1,0,1]
	global_store_dwordx4 v198, v[102:105], s[42:43] offset:192 nt
	global_load_dwordx2 v[148:149], v194, s[40:41] offset:352
	s_waitcnt vmcnt(22)
	v_lshlrev_b32_e32 v206, 16, v150
	v_and_b32_e32 v207, 0xffff0000, v150
	v_lshlrev_b32_e32 v208, 16, v151
	v_and_b32_e32 v209, 0xffff0000, v151
	v_pk_fma_f32 v[98:99], v[206:207], s[76:77], v[98:99] op_sel_hi:[1,0,1]
	v_pk_fma_f32 v[100:101], v[208:209], s[76:77], v[100:101] op_sel_hi:[1,0,1]
	global_store_dwordx4 v199, v[98:101], s[42:43] offset:192 nt
	global_load_dwordx2 v[150:151], v195, s[40:41] offset:352
	s_waitcnt vmcnt(23)
	v_lshlrev_b32_e32 v202, 16, v152
	v_and_b32_e32 v203, 0xffff0000, v152
	v_lshlrev_b32_e32 v204, 16, v153
	v_and_b32_e32 v205, 0xffff0000, v153
	v_pk_fma_f32 v[94:95], v[202:203], s[76:77], v[94:95] op_sel_hi:[1,0,1]
	v_pk_fma_f32 v[96:97], v[204:205], s[76:77], v[96:97] op_sel_hi:[1,0,1]
	global_store_dwordx4 v200, v[94:97], s[42:43] offset:0 nt
	global_load_dwordx2 v[152:153], v196, s[40:41] offset:256
	s_waitcnt vmcnt(24)
	v_lshlrev_b32_e32 v206, 16, v154
	v_and_b32_e32 v207, 0xffff0000, v154
	v_lshlrev_b32_e32 v208, 16, v155
	v_and_b32_e32 v209, 0xffff0000, v155
	v_pk_fma_f32 v[90:91], v[206:207], s[76:77], v[90:91] op_sel_hi:[1,0,1]
	v_pk_fma_f32 v[92:93], v[208:209], s[76:77], v[92:93] op_sel_hi:[1,0,1]
	global_store_dwordx4 v201, v[90:93], s[42:43] offset:0 nt
	global_load_dwordx2 v[154:155], v197, s[40:41] offset:256
	s_waitcnt vmcnt(25)
; __device__ __forceinline__ float bflo(unsigned u) { return __uint_as_float(u << 16); }
; __device__ __forceinline__ float bfhi(unsigned u) { return __uint_as_float(u & 0xffff0000u); }
; __device__ __forceinline__ void epilogue(const Params& p, int mode, const float* resid, int r, int c, f32x4 v) {
;     ...
;   } else if (mode == EPI_RESID_B) {
;     u32x2 xr = *reinterpret_cast<const u32x2*>(WSP(u16, WS_HB) + (long)c * D + r);
;     f32x4 o = {ALPHA * bflo(xr[0]) + v[0], ALPHA * bfhi(xr[0]) + v[1], ALPHA * bflo(xr[1]) + v[2], ALPHA * bfhi(xr[1]) + v[3]};
;     *reinterpret_cast<f32x4*>(WSP(float, WS_PRE) + (long)c * D + r) = o;
; __device__ __forceinline__ void gemm_run(const Params& p, const u16* A1, const u16* Bt1, int M1, int N1, int K, int mode1,
;                                          const float* resid, u16* shm, const u16* A2, const u16* Bt2, int M2, int N2,
;                                          int mode2) {
;     ...
; #pragma unroll
;     for (int ai = 0; ai < 2; ++ai)
; #pragma unroll
;       for (int bj = 0; bj < 2; ++bj)
; #pragma unroll
;         for (int m = 0; m < 4; ++m)
; #pragma unroll
;           for (int n = 0; n < 2; ++n)
;             epilogue(p, mode, resid, brow + ai * HALF + wr * 64 + m * 16 + fq * 4, bcol + bj * HALF + wc * 32 + n * 16 + fr,
;                      acc[ai][bj][m][n]);
	v_lshlrev_b32_e32 v202, 16, v156
	v_and_b32_e32 v203, 0xffff0000, v156
	v_lshlrev_b32_e32 v204, 16, v157
	v_and_b32_e32 v205, 0xffff0000, v157
	v_pk_fma_f32 v[86:87], v[202:203], s[76:77], v[86:87] op_sel_hi:[1,0,1]
	v_pk_fma_f32 v[88:89], v[204:205], s[76:77], v[88:89] op_sel_hi:[1,0,1]
	global_store_dwordx4 v200, v[86:89], s[42:43] offset:64 nt
	global_load_dwordx2 v[156:157], v196, s[40:41] offset:288
	s_waitcnt vmcnt(26)
	v_lshlrev_b32_e32 v206, 16, v158
	v_and_b32_e32 v207, 0xffff0000, v158
	v_lshlrev_b32_e32 v208, 16, v159
	v_and_b32_e32 v209, 0xffff0000, v159
	v_pk_fma_f32 v[82:83], v[206:207], s[76:77], v[82:83] op_sel_hi:[1,0,1]
	v_pk_fma_f32 v[84:85], v[208:209], s[76:77], v[84:85] op_sel_hi:[1,0,1]
	global_store_dwordx4 v201, v[82:85], s[42:43] offset:64 nt
	global_load_dwordx2 v[158:159], v197, s[40:41] offset:288
	s_waitcnt vmcnt(27)
	v_lshlrev_b32_e32 v202, 16, v160
	v_and_b32_e32 v203, 0xffff0000, v160
	v_lshlrev_b32_e32 v204, 16, v161
	v_and_b32_e32 v205, 0xffff0000, v161
	v_pk_fma_f32 v[78:79], v[202:203], s[76:77], v[78:79] op_sel_hi:[1,0,1]
	v_pk_fma_f32 v[80:81], v[204:205], s[76:77], v[80:81] op_sel_hi:[1,0,1]
	global_store_dwordx4 v200, v[78:81], s[42:43] offset:128 nt
	global_load_dwordx2 v[160:161], v196, s[40:41] offset:320
	s_waitcnt vmcnt(28)
	v_lshlrev_b32_e32 v206, 16, v162
	v_and_b32_e32 v207, 0xffff0000, v162
	v_lshlrev_b32_e32 v208, 16, v163
	v_and_b32_e32 v209, 0xffff0000, v163
	v_pk_fma_f32 v[74:75], v[206:207], s[76:77], v[74:75] op_sel_hi:[1,0,1]
	v_pk_fma_f32 v[76:77], v[208:209], s[76:77], v[76:77] op_sel_hi:[1,0,1]
	global_store_dwordx4 v201, v[74:77], s[42:43] offset:128 nt
	global_load_dwordx2 v[162:163], v197, s[40:41] offset:320
	s_waitcnt vmcnt(29)
	v_lshlrev_b32_e32 v202, 16, v190
	v_and_b32_e32 v203, 0xffff0000, v190
	v_lshlrev_b32_e32 v204, 16, v191
	v_and_b32_e32 v205, 0xffff0000, v191
	v_pk_fma_f32 v[70:71], v[202:203], s[76:77], v[70:71] op_sel_hi:[1,0,1]
	v_pk_fma_f32 v[72:73], v[204:205], s[76:77], v[72:73] op_sel_hi:[1,0,1]
	global_store_dwordx4 v200, v[70:73], s[42:43] offset:192 nt
	global_load_dwordx2 v[190:191], v196, s[40:41] offset:352
	s_waitcnt vmcnt(30)
	v_lshlrev_b32_e32 v206, 16, v192
	v_and_b32_e32 v207, 0xffff0000, v192
	v_lshlrev_b32_e32 v208, 16, v193
	v_and_b32_e32 v209, 0xffff0000, v193
	v_pk_fma_f32 v[66:67], v[206:207], s[76:77], v[66:67] op_sel_hi:[1,0,1]
	v_pk_fma_f32 v[68:69], v[208:209], s[76:77], v[68:69] op_sel_hi:[1,0,1]
	global_store_dwordx4 v201, v[66:69], s[42:43] offset:192 nt
	global_load_dwordx2 v[192:193], v197, s[40:41] offset:352
	s_waitcnt vmcnt(30)
	v_lshlrev_b32_e32 v202, 16, v136
	v_and_b32_e32 v203, 0xffff0000, v136
	v_lshlrev_b32_e32 v204, 16, v137
	v_and_b32_e32 v205, 0xffff0000, v137
	v_pk_fma_f32 v[62:63], v[202:203], s[76:77], v[62:63] op_sel_hi:[1,0,1]
	v_pk_fma_f32 v[64:65], v[204:205], s[76:77], v[64:65] op_sel_hi:[1,0,1]
	global_store_dwordx4 v198, v[62:65], s[42:43] offset:512 nt
	s_waitcnt vmcnt(29)
	v_lshlrev_b32_e32 v206, 16, v138
	v_and_b32_e32 v207, 0xffff0000, v138
	v_lshlrev_b32_e32 v208, 16, v139
	v_and_b32_e32 v209, 0xffff0000, v139
	v_pk_fma_f32 v[58:59], v[206:207], s[76:77], v[58:59] op_sel_hi:[1,0,1]
	v_pk_fma_f32 v[60:61], v[208:209], s[76:77], v[60:61] op_sel_hi:[1,0,1]
	global_store_dwordx4 v199, v[58:61], s[42:43] offset:512 nt
	s_waitcnt vmcnt(28)
	v_lshlrev_b32_e32 v202, 16, v140
	v_and_b32_e32 v203, 0xffff0000, v140
	v_lshlrev_b32_e32 v204, 16, v141
	v_and_b32_e32 v205, 0xffff0000, v141
	v_pk_fma_f32 v[54:55], v[202:203], s[76:77], v[54:55] op_sel_hi:[1,0,1]
	v_pk_fma_f32 v[56:57], v[204:205], s[76:77], v[56:57] op_sel_hi:[1,0,1]
	global_store_dwordx4 v198, v[54:57], s[42:43] offset:576 nt
	s_waitcnt vmcnt(27)
	v_lshlrev_b32_e32 v206, 16, v142
	v_and_b32_e32 v207, 0xffff0000, v142
	v_lshlrev_b32_e32 v208, 16, v143
	v_and_b32_e32 v209, 0xffff0000, v143
	v_pk_fma_f32 v[50:51], v[206:207], s[76:77], v[50:51] op_sel_hi:[1,0,1]
	v_pk_fma_f32 v[52:53], v[208:209], s[76:77], v[52:53] op_sel_hi:[1,0,1]
	global_store_dwordx4 v199, v[50:53], s[42:43] offset:576 nt
	s_waitcnt vmcnt(26)
	v_lshlrev_b32_e32 v202, 16, v144
	v_and_b32_e32 v203, 0xffff0000, v144
	v_lshlrev_b32_e32 v204, 16, v145
	v_and_b32_e32 v205, 0xffff0000, v145
	v_pk_fma_f32 v[46:47], v[202:203], s[76:77], v[46:47] op_sel_hi:[1,0,1]
	v_pk_fma_f32 v[48:49], v[204:205], s[76:77], v[48:49] op_sel_hi:[1,0,1]
	global_store_dwordx4 v198, v[46:49], s[42:43] offset:640 nt
	s_waitcnt vmcnt(25)
	v_lshlrev_b32_e32 v206, 16, v146
	v_and_b32_e32 v207, 0xffff0000, v146
	v_lshlrev_b32_e32 v208, 16, v147
	v_and_b32_e32 v209, 0xffff0000, v147
	v_pk_fma_f32 v[42:43], v[206:207], s[76:77], v[42:43] op_sel_hi:[1,0,1]
	v_pk_fma_f32 v[44:45], v[208:209], s[76:77], v[44:45] op_sel_hi:[1,0,1]
	global_store_dwordx4 v199, v[42:45], s[42:43] offset:640 nt
	s_waitcnt vmcnt(24)
	v_lshlrev_b32_e32 v202, 16, v148
	v_and_b32_e32 v203, 0xffff0000, v148
	v_lshlrev_b32_e32 v204, 16, v149
	v_and_b32_e32 v205, 0xffff0000, v149
	v_pk_fma_f32 v[38:39], v[202:203], s[76:77], v[38:39] op_sel_hi:[1,0,1]
	v_pk_fma_f32 v[40:41], v[204:205], s[76:77], v[40:41] op_sel_hi:[1,0,1]
	global_store_dwordx4 v198, v[38:41], s[42:43] offset:704 nt
	s_waitcnt vmcnt(23)
	v_lshlrev_b32_e32 v206, 16, v150
	v_and_b32_e32 v207, 0xffff0000, v150
	v_lshlrev_b32_e32 v208, 16, v151
	v_and_b32_e32 v209, 0xffff0000, v151
	v_pk_fma_f32 v[34:35], v[206:207], s[76:77], v[34:35] op_sel_hi:[1,0,1]
	v_pk_fma_f32 v[36:37], v[208:209], s[76:77], v[36:37] op_sel_hi:[1,0,1]
	global_store_dwordx4 v199, v[34:37], s[42:43] offset:704 nt
	s_waitcnt vmcnt(22)
; __device__ __forceinline__ void epilogue(const Params& p, int mode, const float* resid, int r, int c, f32x4 v) {
;     ...
;   } else if (mode == EPI_RESID) {
;     f32x4 x = __builtin_nontemporal_load(reinterpret_cast<const f32x4*>(resid + (long)c * D + r));
;     f32x4 o = {ALPHA * x[0] + v[0], ALPHA * x[1] + v[1], ALPHA * x[2] + v[2], ALPHA * x[3] + v[3]};
;     *reinterpret_cast<f32x4*>(WSP(float, WS_PRE) + (long)c * D + r) = o;
; __device__ __forceinline__ void gemm_run(const Params& p, const u16* A1, const u16* Bt1, int M1, int N1, int K, int mode1,
;                                          const float* resid, u16* shm, const u16* A2, const u16* Bt2, int M2, int N2,
;                                          int mode2) {
;     ...
; #pragma unroll
;     for (int ai = 0; ai < 2; ++ai)
; #pragma unroll
;       for (int bj = 0; bj < 2; ++bj)
; #pragma unroll
;         for (int m = 0; m < 4; ++m)
; #pragma unroll
;           for (int n = 0; n < 2; ++n)
;             epilogue(p, mode, resid, brow + ai * HALF + wr * 64 + m * 16 + fq * 4, bcol + bj * HALF + wc * 32 + n * 16 + fr,
;                      acc[ai][bj][m][n]);
	v_lshlrev_b32_e32 v202, 16, v152
	v_and_b32_e32 v203, 0xffff0000, v152
	v_lshlrev_b32_e32 v204, 16, v153
	v_and_b32_e32 v205, 0xffff0000, v153
	v_pk_fma_f32 v[30:31], v[202:203], s[76:77], v[30:31] op_sel_hi:[1,0,1]
	v_pk_fma_f32 v[32:33], v[204:205], s[76:77], v[32:33] op_sel_hi:[1,0,1]
	global_store_dwordx4 v200, v[30:33], s[42:43] offset:512 nt
	s_waitcnt vmcnt(21)
	v_lshlrev_b32_e32 v206, 16, v154
	v_and_b32_e32 v207, 0xffff0000, v154
	v_lshlrev_b32_e32 v208, 16, v155
	v_and_b32_e32 v209, 0xffff0000, v155
	v_pk_fma_f32 v[26:27], v[206:207], s[76:77], v[26:27] op_sel_hi:[1,0,1]
	v_pk_fma_f32 v[28:29], v[208:209], s[76:77], v[28:29] op_sel_hi:[1,0,1]
	global_store_dwordx4 v201, v[26:29], s[42:43] offset:512 nt
	s_waitcnt vmcnt(20)
	v_lshlrev_b32_e32 v202, 16, v156
	v_and_b32_e32 v203, 0xffff0000, v156
	v_lshlrev_b32_e32 v204, 16, v157
	v_and_b32_e32 v205, 0xffff0000, v157
	v_pk_fma_f32 v[22:23], v[202:203], s[76:77], v[22:23] op_sel_hi:[1,0,1]
	v_pk_fma_f32 v[24:25], v[204:205], s[76:77], v[24:25] op_sel_hi:[1,0,1]
	global_store_dwordx4 v200, v[22:25], s[42:43] offset:576 nt
	s_waitcnt vmcnt(19)
	v_lshlrev_b32_e32 v206, 16, v158
	v_and_b32_e32 v207, 0xffff0000, v158
	v_lshlrev_b32_e32 v208, 16, v159
	v_and_b32_e32 v209, 0xffff0000, v159
	v_pk_fma_f32 v[18:19], v[206:207], s[76:77], v[18:19] op_sel_hi:[1,0,1]
	v_pk_fma_f32 v[20:21], v[208:209], s[76:77], v[20:21] op_sel_hi:[1,0,1]
	global_store_dwordx4 v201, v[18:21], s[42:43] offset:576 nt
	s_waitcnt vmcnt(18)
	v_lshlrev_b32_e32 v202, 16, v160
	v_and_b32_e32 v203, 0xffff0000, v160
	v_lshlrev_b32_e32 v204, 16, v161
	v_and_b32_e32 v205, 0xffff0000, v161
	v_pk_fma_f32 v[14:15], v[202:203], s[76:77], v[14:15] op_sel_hi:[1,0,1]
	v_pk_fma_f32 v[16:17], v[204:205], s[76:77], v[16:17] op_sel_hi:[1,0,1]
	global_store_dwordx4 v200, v[14:17], s[42:43] offset:640 nt
	s_waitcnt vmcnt(17)
	v_lshlrev_b32_e32 v206, 16, v162
	v_and_b32_e32 v207, 0xffff0000, v162
	v_lshlrev_b32_e32 v208, 16, v163
	v_and_b32_e32 v209, 0xffff0000, v163
	v_pk_fma_f32 v[10:11], v[206:207], s[76:77], v[10:11] op_sel_hi:[1,0,1]
	v_pk_fma_f32 v[12:13], v[208:209], s[76:77], v[12:13] op_sel_hi:[1,0,1]
	global_store_dwordx4 v201, v[10:13], s[42:43] offset:640 nt
	s_waitcnt vmcnt(16)
	v_lshlrev_b32_e32 v202, 16, v190
	v_and_b32_e32 v203, 0xffff0000, v190
	v_lshlrev_b32_e32 v204, 16, v191
	v_and_b32_e32 v205, 0xffff0000, v191
	v_pk_fma_f32 v[6:7], v[202:203], s[76:77], v[6:7] op_sel_hi:[1,0,1]
	v_pk_fma_f32 v[8:9], v[204:205], s[76:77], v[8:9] op_sel_hi:[1,0,1]
	global_store_dwordx4 v200, v[6:9], s[42:43] offset:704 nt
	s_waitcnt vmcnt(15)
	v_lshlrev_b32_e32 v206, 16, v192
	v_and_b32_e32 v207, 0xffff0000, v192
	v_lshlrev_b32_e32 v208, 16, v193
	v_and_b32_e32 v209, 0xffff0000, v193
	v_pk_fma_f32 v[2:3], v[206:207], s[76:77], v[2:3] op_sel_hi:[1,0,1]
	v_pk_fma_f32 v[4:5], v[208:209], s[76:77], v[4:5] op_sel_hi:[1,0,1]
	global_store_dwordx4 v201, v[2:5], s[42:43] offset:704 nt
	s_branch .LBB0_382
.Lepi2_start:
	v_add_u32_e32 v0, s74, v187
	v_or_b32_e32 v0, v0, v188
	v_or_b32_e32 v130, s91, v189
	v_lshlrev_b32_e32 v0, 2, v0
	v_lshl_add_u32 v0, v130, 14, v0
	v_add_u32_e32 v130, 0x40000, v0
	v_add_u32_e32 v131, 0x200000, v0
	v_add_u32_e32 v164, 0x240000, v0
	global_load_dwordx4 v[136:139], v0, s[28:29] offset:0 nt
	global_load_dwordx4 v[140:143], v130, s[28:29] offset:0 nt
	global_load_dwordx4 v[144:147], v0, s[28:29] offset:64 nt
	global_load_dwordx4 v[148:151], v130, s[28:29] offset:64 nt
	global_load_dwordx4 v[152:155], v0, s[28:29] offset:128 nt
	global_load_dwordx4 v[156:159], v130, s[28:29] offset:128 nt
	global_load_dwordx4 v[160:163], v0, s[28:29] offset:192 nt
	global_load_dwordx4 v[190:193], v130, s[28:29] offset:192 nt
	global_load_dwordx4 v[194:197], v131, s[28:29] offset:0 nt
	global_load_dwordx4 v[198:201], v164, s[28:29] offset:0 nt
	global_load_dwordx4 v[202:205], v131, s[28:29] offset:64 nt
	global_load_dwordx4 v[206:209], v164, s[28:29] offset:64 nt
	global_load_dwordx4 v[210:213], v131, s[28:29] offset:128 nt
	global_load_dwordx4 v[214:217], v164, s[28:29] offset:128 nt
	global_load_dwordx4 v[218:221], v131, s[28:29] offset:192 nt
	global_load_dwordx4 v[222:225], v164, s[28:29] offset:192 nt
	s_waitcnt vmcnt(15)
	v_pk_fma_f32 v[126:127], v[136:137], s[76:77], v[126:127] op_sel_hi:[1,0,1]
	v_pk_fma_f32 v[128:129], v[138:139], s[76:77], v[128:129] op_sel_hi:[1,0,1]
	global_store_dwordx4 v0, v[126:129], s[42:43] offset:0 nt
	global_load_dwordx4 v[136:139], v0, s[28:29] offset:512 nt
	s_waitcnt vmcnt(16)
	v_pk_fma_f32 v[122:123], v[140:141], s[76:77], v[122:123] op_sel_hi:[1,0,1]
	v_pk_fma_f32 v[124:125], v[142:143], s[76:77], v[124:125] op_sel_hi:[1,0,1]
	global_store_dwordx4 v130, v[122:125], s[42:43] offset:0 nt
	global_load_dwordx4 v[140:143], v130, s[28:29] offset:512 nt
	s_waitcnt vmcnt(17)
	v_pk_fma_f32 v[118:119], v[144:145], s[76:77], v[118:119] op_sel_hi:[1,0,1]
	v_pk_fma_f32 v[120:121], v[146:147], s[76:77], v[120:121] op_sel_hi:[1,0,1]
	global_store_dwordx4 v0, v[118:121], s[42:43] offset:64 nt
	global_load_dwordx4 v[144:147], v0, s[28:29] offset:576 nt
	s_waitcnt vmcnt(18)
	v_pk_fma_f32 v[114:115], v[148:149], s[76:77], v[114:115] op_sel_hi:[1,0,1]
	v_pk_fma_f32 v[116:117], v[150:151], s[76:77], v[116:117] op_sel_hi:[1,0,1]
	global_store_dwordx4 v130, v[114:117], s[42:43] offset:64 nt
	global_load_dwordx4 v[148:151], v130, s[28:29] offset:576 nt
	s_waitcnt vmcnt(19)
	v_pk_fma_f32 v[110:111], v[152:153], s[76:77], v[110:111] op_sel_hi:[1,0,1]
	v_pk_fma_f32 v[112:113], v[154:155], s[76:77], v[112:113] op_sel_hi:[1,0,1]
	global_store_dwordx4 v0, v[110:113], s[42:43] offset:128 nt
	global_load_dwordx4 v[152:155], v0, s[28:29] offset:640 nt
	s_waitcnt vmcnt(20)
; __device__ __forceinline__ void epilogue(const Params& p, int mode, const float* resid, int r, int c, f32x4 v) {
;     ...
;   } else if (mode == EPI_RESID) {
;     f32x4 x = __builtin_nontemporal_load(reinterpret_cast<const f32x4*>(resid + (long)c * D + r));
;     f32x4 o = {ALPHA * x[0] + v[0], ALPHA * x[1] + v[1], ALPHA * x[2] + v[2], ALPHA * x[3] + v[3]};
;     *reinterpret_cast<f32x4*>(WSP(float, WS_PRE) + (long)c * D + r) = o;
; __device__ __forceinline__ void gemm_run(const Params& p, const u16* A1, const u16* Bt1, int M1, int N1, int K, int mode1,
;                                          const float* resid, u16* shm, const u16* A2, const u16* Bt2, int M2, int N2,
;                                          int mode2) {
;     ...
; #pragma unroll
;     for (int ai = 0; ai < 2; ++ai)
; #pragma unroll
;       for (int bj = 0; bj < 2; ++bj)
; #pragma unroll
;         for (int m = 0; m < 4; ++m)
; #pragma unroll
;           for (int n = 0; n < 2; ++n)
;             epilogue(p, mode, resid, brow + ai * HALF + wr * 64 + m * 16 + fq * 4, bcol + bj * HALF + wc * 32 + n * 16 + fr,
;                      acc[ai][bj][m][n]);
	v_pk_fma_f32 v[106:107], v[156:157], s[76:77], v[106:107] op_sel_hi:[1,0,1]
	v_pk_fma_f32 v[108:109], v[158:159], s[76:77], v[108:109] op_sel_hi:[1,0,1]
	global_store_dwordx4 v130, v[106:109], s[42:43] offset:128 nt
	global_load_dwordx4 v[156:159], v130, s[28:29] offset:640 nt
	s_waitcnt vmcnt(21)
	v_pk_fma_f32 v[102:103], v[160:161], s[76:77], v[102:103] op_sel_hi:[1,0,1]
	v_pk_fma_f32 v[104:105], v[162:163], s[76:77], v[104:105] op_sel_hi:[1,0,1]
	global_store_dwordx4 v0, v[102:105], s[42:43] offset:192 nt
	global_load_dwordx4 v[160:163], v0, s[28:29] offset:704 nt
	s_waitcnt vmcnt(22)
	v_pk_fma_f32 v[98:99], v[190:191], s[76:77], v[98:99] op_sel_hi:[1,0,1]
	v_pk_fma_f32 v[100:101], v[192:193], s[76:77], v[100:101] op_sel_hi:[1,0,1]
	global_store_dwordx4 v130, v[98:101], s[42:43] offset:192 nt
	global_load_dwordx4 v[190:193], v130, s[28:29] offset:704 nt
	s_waitcnt vmcnt(23)
	v_pk_fma_f32 v[94:95], v[194:195], s[76:77], v[94:95] op_sel_hi:[1,0,1]
	v_pk_fma_f32 v[96:97], v[196:197], s[76:77], v[96:97] op_sel_hi:[1,0,1]
	global_store_dwordx4 v131, v[94:97], s[42:43] offset:0 nt
	global_load_dwordx4 v[194:197], v131, s[28:29] offset:512 nt
	s_waitcnt vmcnt(24)
	v_pk_fma_f32 v[90:91], v[198:199], s[76:77], v[90:91] op_sel_hi:[1,0,1]
	v_pk_fma_f32 v[92:93], v[200:201], s[76:77], v[92:93] op_sel_hi:[1,0,1]
	global_store_dwordx4 v164, v[90:93], s[42:43] offset:0 nt
	global_load_dwordx4 v[198:201], v164, s[28:29] offset:512 nt
	s_waitcnt vmcnt(25)
	v_pk_fma_f32 v[86:87], v[202:203], s[76:77], v[86:87] op_sel_hi:[1,0,1]
	v_pk_fma_f32 v[88:89], v[204:205], s[76:77], v[88:89] op_sel_hi:[1,0,1]
	global_store_dwordx4 v131, v[86:89], s[42:43] offset:64 nt
	global_load_dwordx4 v[202:205], v131, s[28:29] offset:576 nt
	s_waitcnt vmcnt(26)
	v_pk_fma_f32 v[82:83], v[206:207], s[76:77], v[82:83] op_sel_hi:[1,0,1]
	v_pk_fma_f32 v[84:85], v[208:209], s[76:77], v[84:85] op_sel_hi:[1,0,1]
	global_store_dwordx4 v164, v[82:85], s[42:43] offset:64 nt
	global_load_dwordx4 v[206:209], v164, s[28:29] offset:576 nt
	s_waitcnt vmcnt(27)
	v_pk_fma_f32 v[78:79], v[210:211], s[76:77], v[78:79] op_sel_hi:[1,0,1]
	v_pk_fma_f32 v[80:81], v[212:213], s[76:77], v[80:81] op_sel_hi:[1,0,1]
	global_store_dwordx4 v131, v[78:81], s[42:43] offset:128 nt
	global_load_dwordx4 v[210:213], v131, s[28:29] offset:640 nt
	s_waitcnt vmcnt(28)
	v_pk_fma_f32 v[74:75], v[214:215], s[76:77], v[74:75] op_sel_hi:[1,0,1]
	v_pk_fma_f32 v[76:77], v[216:217], s[76:77], v[76:77] op_sel_hi:[1,0,1]
	global_store_dwordx4 v164, v[74:77], s[42:43] offset:128 nt
	global_load_dwordx4 v[214:217], v164, s[28:29] offset:640 nt
	s_waitcnt vmcnt(29)
	v_pk_fma_f32 v[70:71], v[218:219], s[76:77], v[70:71] op_sel_hi:[1,0,1]
	v_pk_fma_f32 v[72:73], v[220:221], s[76:77], v[72:73] op_sel_hi:[1,0,1]
	global_store_dwordx4 v131, v[70:73], s[42:43] offset:192 nt
	global_load_dwordx4 v[218:221], v131, s[28:29] offset:704 nt
	s_waitcnt vmcnt(30)
	v_pk_fma_f32 v[66:67], v[222:223], s[76:77], v[66:67] op_sel_hi:[1,0,1]
	v_pk_fma_f32 v[68:69], v[224:225], s[76:77], v[68:69] op_sel_hi:[1,0,1]
	global_store_dwordx4 v164, v[66:69], s[42:43] offset:192 nt
	global_load_dwordx4 v[222:225], v164, s[28:29] offset:704 nt
	s_waitcnt vmcnt(30)
	v_pk_fma_f32 v[62:63], v[136:137], s[76:77], v[62:63] op_sel_hi:[1,0,1]
	v_pk_fma_f32 v[64:65], v[138:139], s[76:77], v[64:65] op_sel_hi:[1,0,1]
	global_store_dwordx4 v0, v[62:65], s[42:43] offset:512 nt
	s_waitcnt vmcnt(29)
	v_pk_fma_f32 v[58:59], v[140:141], s[76:77], v[58:59] op_sel_hi:[1,0,1]
	v_pk_fma_f32 v[60:61], v[142:143], s[76:77], v[60:61] op_sel_hi:[1,0,1]
	global_store_dwordx4 v130, v[58:61], s[42:43] offset:512 nt
	s_waitcnt vmcnt(28)
	v_pk_fma_f32 v[54:55], v[144:145], s[76:77], v[54:55] op_sel_hi:[1,0,1]
	v_pk_fma_f32 v[56:57], v[146:147], s[76:77], v[56:57] op_sel_hi:[1,0,1]
	global_store_dwordx4 v0, v[54:57], s[42:43] offset:576 nt
	s_waitcnt vmcnt(27)
	v_pk_fma_f32 v[50:51], v[148:149], s[76:77], v[50:51] op_sel_hi:[1,0,1]
	v_pk_fma_f32 v[52:53], v[150:151], s[76:77], v[52:53] op_sel_hi:[1,0,1]
	global_store_dwordx4 v130, v[50:53], s[42:43] offset:576 nt
	s_waitcnt vmcnt(26)
	v_pk_fma_f32 v[46:47], v[152:153], s[76:77], v[46:47] op_sel_hi:[1,0,1]
	v_pk_fma_f32 v[48:49], v[154:155], s[76:77], v[48:49] op_sel_hi:[1,0,1]
	global_store_dwordx4 v0, v[46:49], s[42:43] offset:640 nt
	s_waitcnt vmcnt(25)
	v_pk_fma_f32 v[42:43], v[156:157], s[76:77], v[42:43] op_sel_hi:[1,0,1]
	v_pk_fma_f32 v[44:45], v[158:159], s[76:77], v[44:45] op_sel_hi:[1,0,1]
	global_store_dwordx4 v130, v[42:45], s[42:43] offset:640 nt
	s_waitcnt vmcnt(24)
	v_pk_fma_f32 v[38:39], v[160:161], s[76:77], v[38:39] op_sel_hi:[1,0,1]
	v_pk_fma_f32 v[40:41], v[162:163], s[76:77], v[40:41] op_sel_hi:[1,0,1]
	global_store_dwordx4 v0, v[38:41], s[42:43] offset:704 nt
	s_waitcnt vmcnt(23)
	v_pk_fma_f32 v[34:35], v[190:191], s[76:77], v[34:35] op_sel_hi:[1,0,1]
	v_pk_fma_f32 v[36:37], v[192:193], s[76:77], v[36:37] op_sel_hi:[1,0,1]
	global_store_dwordx4 v130, v[34:37], s[42:43] offset:704 nt
	s_waitcnt vmcnt(22)
	v_pk_fma_f32 v[30:31], v[194:195], s[76:77], v[30:31] op_sel_hi:[1,0,1]
	v_pk_fma_f32 v[32:33], v[196:197], s[76:77], v[32:33] op_sel_hi:[1,0,1]
	global_store_dwordx4 v131, v[30:33], s[42:43] offset:512 nt
	s_waitcnt vmcnt(21)
	v_pk_fma_f32 v[26:27], v[198:199], s[76:77], v[26:27] op_sel_hi:[1,0,1]
	v_pk_fma_f32 v[28:29], v[200:201], s[76:77], v[28:29] op_sel_hi:[1,0,1]
	global_store_dwordx4 v164, v[26:29], s[42:43] offset:512 nt
	s_waitcnt vmcnt(20)
	v_pk_fma_f32 v[22:23], v[202:203], s[76:77], v[22:23] op_sel_hi:[1,0,1]
	v_pk_fma_f32 v[24:25], v[204:205], s[76:77], v[24:25] op_sel_hi:[1,0,1]
	global_store_dwordx4 v131, v[22:25], s[42:43] offset:576 nt
	s_waitcnt vmcnt(19)
	v_pk_fma_f32 v[18:19], v[206:207], s[76:77], v[18:19] op_sel_hi:[1,0,1]
	v_pk_fma_f32 v[20:21], v[208:209], s[76:77], v[20:21] op_sel_hi:[1,0,1]
	global_store_dwordx4 v164, v[18:21], s[42:43] offset:576 nt
	s_waitcnt vmcnt(18)
	v_pk_fma_f32 v[14:15], v[210:211], s[76:77], v[14:15] op_sel_hi:[1,0,1]
	v_pk_fma_f32 v[16:17], v[212:213], s[76:77], v[16:17] op_sel_hi:[1,0,1]
	global_store_dwordx4 v131, v[14:17], s[42:43] offset:640 nt
	s_waitcnt vmcnt(17)
	v_pk_fma_f32 v[10:11], v[214:215], s[76:77], v[10:11] op_sel_hi:[1,0,1]
	v_pk_fma_f32 v[12:13], v[216:217], s[76:77], v[12:13] op_sel_hi:[1,0,1]
	global_store_dwordx4 v164, v[10:13], s[42:43] offset:640 nt
	s_waitcnt vmcnt(16)
	v_pk_fma_f32 v[6:7], v[218:219], s[76:77], v[6:7] op_sel_hi:[1,0,1]
	v_pk_fma_f32 v[8:9], v[220:221], s[76:77], v[8:9] op_sel_hi:[1,0,1]
	global_store_dwordx4 v131, v[6:9], s[42:43] offset:704 nt
	s_waitcnt vmcnt(15)
	v_pk_fma_f32 v[2:3], v[222:223], s[76:77], v[2:3] op_sel_hi:[1,0,1]
	v_pk_fma_f32 v[4:5], v[224:225], s[76:77], v[4:5] op_sel_hi:[1,0,1]
	global_store_dwordx4 v164, v[2:5], s[42:43] offset:704 nt
	s_branch .LBB0_382
